# nt hint also on the once-read ybuf load of the ssd4 phase
# baseline (speedup 1.0000x reference)
; DI float wave_sum(float v) { for (int o = 32; o > 0; o >>= 1) v += __shfl_xor(v, o); return v; }
; DI float siluf(float x) { return x / (1.f + __expf(-x)); }
; DI void phase_ssd4(PP p, int l, bool need_ctx) {
;     ...
;     int t = r % TT; if (t < CTX && !need_ctx) continue;
;     U4 yv = *(const U4*)(ybuf + (size_t)r * 512 + lane * 8), zv = *(const U4*)(zx + (size_t)r * 1536 + lane * 8);
;     float y[8], z[8]; unpack8(yv, y); unpack8(zv, z);
;     float ss = 0.f;
; #pragma unroll
;     for (int e = 0; e < 8; ++e) { y[e] *= siluf(z[e]); ss += y[e] * y[e]; }
;     ss = wave_sum(ss); float rstd = rsqrtf(ss * (1.f / 512.f) + EPS);
.LBB0_274:
	s_mov_b32 s4, 0x3e0f83e1
	v_mul_hi_i32 v0, v16, s4
	v_lshrrev_b32_e32 v2, 31, v0
	v_ashrrev_i32_e32 v0, 11, v0
	v_add_u32_e32 v0, v0, v2
	v_mul_i32_i24_e32 v0, 0x2100, v0
	v_sub_u32_e32 v0, v16, v0
	s_movk_i32 s4, 0xff
	v_cmp_lt_i32_e32 vcc, s4, v0
	s_xor_b64 s[4:5], s[26:27], -1
	s_or_b64 s[6:7], s[4:5], vcc
	s_and_saveexec_b64 s[4:5], s[6:7]
	s_cbranch_execz .LBB0_273
	v_ashrrev_i32_e32 v17, 31, v16
	v_lshlrev_b64 v[2:3], 10, v[16:17]
	s_movk_i32 s6, 0xc00
	v_lshl_add_u64 v[2:3], v[18:19], 0, v[2:3]
	v_mad_i64_i32 v[24:25], s[6:7], v16, s6, v[20:21]
	global_load_dwordx4 v[6:9], v[2:3], off nt
	v_and_b32_e32 v0, 64, v205
	global_load_dwordx4 v[2:5], v[24:25], off
	v_add_u32_e32 v0, 64, v0
	v_xor_b32_e32 v10, 32, v205
	v_cmp_lt_i32_e32 vcc, v10, v0
	s_waitcnt vmcnt(1)
	v_and_b32_e32 v11, 0xffff0000, v9
	v_cndmask_b32_e32 v10, v205, v10, vcc
	v_lshlrev_b32_e32 v39, 2, v10
	v_xor_b32_e32 v10, 16, v205
	v_cmp_lt_i32_e32 vcc, v10, v0
	v_lshlrev_b32_e32 v32, 16, v7
	v_and_b32_e32 v33, 0xffff0000, v7
	v_cndmask_b32_e32 v10, v205, v10, vcc
	v_lshlrev_b32_e32 v38, 2, v10
	v_xor_b32_e32 v10, 8, v205
	v_cmp_lt_i32_e32 vcc, v10, v0
	s_waitcnt vmcnt(0)
	v_lshlrev_b32_e32 v7, 16, v3
	v_and_b32_e32 v3, 0xffff0000, v3
	v_cndmask_b32_e32 v10, v205, v10, vcc
	v_lshlrev_b32_e32 v37, 2, v10
	v_xor_b32_e32 v10, 4, v205
	v_cmp_lt_i32_e32 vcc, v10, v0
	v_mul_f32_e32 v34, 0xbfb8aa3b, v7
	v_mul_f32_e32 v35, 0xbfb8aa3b, v3
	v_cndmask_b32_e32 v10, v205, v10, vcc
	v_lshlrev_b32_e32 v36, 2, v10
	v_xor_b32_e32 v10, 2, v205
	v_cmp_lt_i32_e32 vcc, v10, v0
	v_exp_f32_e32 v34, v34
	v_exp_f32_e32 v35, v35
	v_cndmask_b32_e32 v10, v205, v10, vcc
	v_lshlrev_b32_e32 v17, 2, v10
	v_xor_b32_e32 v10, 1, v205
	v_cmp_lt_i32_e32 vcc, v10, v0
	v_pk_add_f32 v[34:35], v[34:35], 1.0 op_sel_hi:[1,0]
	s_nop 0
	v_cndmask_b32_e32 v0, v205, v10, vcc
	v_lshlrev_b32_e32 v10, 16, v9
	v_lshlrev_b32_e32 v9, 16, v5
	v_and_b32_e32 v5, 0xffff0000, v5
	v_mul_f32_e32 v12, 0xbfb8aa3b, v9
	v_mul_f32_e32 v13, 0xbfb8aa3b, v5
	v_exp_f32_e32 v12, v12
	v_exp_f32_e32 v13, v13
	v_div_scale_f32 v40, s[6:7], v35, v35, v3
	v_rcp_f32_e32 v41, v40
	v_pk_add_f32 v[12:13], v[12:13], 1.0 op_sel_hi:[1,0]
	v_lshlrev_b32_e32 v0, 2, v0
	v_div_scale_f32 v14, s[6:7], v13, v13, v5
	v_rcp_f32_e32 v15, v14
	v_fma_f32 v42, -v40, v41, 1.0
	v_fmac_f32_e32 v41, v42, v41
	v_fma_f32 v26, -v14, v15, 1.0
	v_fmac_f32_e32 v15, v26, v15
	v_div_scale_f32 v26, vcc, v5, v13, v5
	v_mul_f32_e32 v27, v26, v15
	v_fma_f32 v28, -v14, v27, v26
	v_fmac_f32_e32 v27, v28, v15
	v_fma_f32 v14, -v14, v27, v26
	v_div_fmas_f32 v14, v14, v15, v27
	v_div_fixup_f32 v13, v14, v13, v5
	v_div_scale_f32 v5, s[6:7], v12, v12, v9
	v_rcp_f32_e32 v14, v5
	s_nop 0
	v_fma_f32 v15, -v5, v14, 1.0
	v_fmac_f32_e32 v14, v15, v14
	v_div_scale_f32 v15, vcc, v9, v12, v9
	v_mul_f32_e32 v26, v15, v14
	v_fma_f32 v27, -v5, v26, v15
	v_fmac_f32_e32 v26, v27, v14
	v_fma_f32 v5, -v5, v26, v15
	v_div_fmas_f32 v5, v5, v14, v26
	v_div_fixup_f32 v12, v5, v12, v9
	v_pk_mul_f32 v[26:27], v[12:13], v[10:11]
	v_lshlrev_b32_e32 v10, 16, v8
	v_and_b32_e32 v11, 0xffff0000, v8
	v_lshlrev_b32_e32 v8, 16, v4
	v_and_b32_e32 v9, 0xffff0000, v4
	v_mul_f32_e32 v4, 0xbfb8aa3b, v8
	v_mul_f32_e32 v5, 0xbfb8aa3b, v9
	v_exp_f32_e32 v4, v4
	v_exp_f32_e32 v5, v5
	v_pk_mul_f32 v[28:29], v[26:27], v[26:27]
	v_pk_add_f32 v[4:5], v[4:5], 1.0 op_sel_hi:[1,0]
	s_nop 0
	v_div_scale_f32 v12, s[6:7], v5, v5, v9
	v_rcp_f32_e32 v13, v12
	s_nop 0
	v_fma_f32 v14, -v12, v13, 1.0
	v_fmac_f32_e32 v13, v14, v13
	v_div_scale_f32 v14, vcc, v9, v5, v9
	v_mul_f32_e32 v15, v14, v13
	v_fma_f32 v30, -v12, v15, v14
	v_fmac_f32_e32 v15, v30, v13
	v_fma_f32 v12, -v12, v15, v14
	v_div_fmas_f32 v12, v12, v13, v15
	v_div_fixup_f32 v5, v12, v5, v9
	v_div_scale_f32 v9, s[6:7], v4, v4, v8
	v_rcp_f32_e32 v12, v9
	s_nop 0
	v_fma_f32 v13, -v9, v12, 1.0
	v_fmac_f32_e32 v12, v13, v12
	v_div_scale_f32 v13, vcc, v8, v4, v8
	v_mul_f32_e32 v14, v13, v12
	v_fma_f32 v15, -v9, v14, v13
	v_fmac_f32_e32 v14, v15, v12
	v_fma_f32 v9, -v9, v14, v13
	v_div_fmas_f32 v9, v9, v12, v14
	v_div_scale_f32 v42, vcc, v3, v35, v3
	v_mul_f32_e32 v43, v42, v41
	v_fma_f32 v44, -v40, v43, v42
	v_fmac_f32_e32 v43, v44, v41
	v_fma_f32 v40, -v40, v43, v42
	v_div_fmas_f32 v40, v40, v41, v43
	v_div_fixup_f32 v35, v40, v35, v3
	v_div_scale_f32 v3, s[6:7], v34, v34, v7
	v_rcp_f32_e32 v40, v3
	v_div_fixup_f32 v4, v9, v4, v8
	v_pk_mul_f32 v[4:5], v[4:5], v[10:11]
	global_load_dwordx4 v[8:11], v[22:23], off offset:16
	global_load_dwordx4 v[12:15], v[22:23], off
	v_fma_f32 v41, -v3, v40, 1.0
	v_fmac_f32_e32 v40, v41, v40
	v_div_scale_f32 v41, vcc, v7, v34, v7
	v_mul_f32_e32 v42, v41, v40
	v_fma_f32 v43, -v3, v42, v41
	v_fmac_f32_e32 v42, v43, v40
	v_fma_f32 v3, -v3, v42, v41
	v_div_fmas_f32 v3, v3, v40, v42
	v_div_fixup_f32 v34, v3, v34, v7
	v_lshlrev_b32_e32 v40, 16, v6
	v_and_b32_e32 v41, 0xffff0000, v6
	v_lshlrev_b32_e32 v6, 16, v2
	v_and_b32_e32 v7, 0xffff0000, v2
	v_mul_f32_e32 v2, 0xbfb8aa3b, v6
	v_mul_f32_e32 v3, 0xbfb8aa3b, v7
	v_exp_f32_e32 v2, v2
	v_exp_f32_e32 v3, v3
	v_pk_mul_f32 v[32:33], v[34:35], v[32:33]
	v_pk_mul_f32 v[30:31], v[4:5], v[4:5]
	v_pk_mul_f32 v[34:35], v[32:33], v[32:33]
	v_pk_add_f32 v[2:3], v[2:3], 1.0 op_sel_hi:[1,0]
	s_nop 0
	v_div_scale_f32 v42, s[6:7], v3, v3, v7
	v_rcp_f32_e32 v43, v42
	s_nop 0
	v_fma_f32 v44, -v42, v43, 1.0
	v_fmac_f32_e32 v43, v44, v43
	v_div_scale_f32 v44, vcc, v7, v3, v7
	v_mul_f32_e32 v45, v44, v43
	v_fma_f32 v46, -v42, v45, v44
	v_fmac_f32_e32 v45, v46, v43
	v_fma_f32 v42, -v42, v45, v44
	v_div_fmas_f32 v42, v42, v43, v45
	v_div_fixup_f32 v3, v42, v3, v7
	v_div_scale_f32 v7, s[6:7], v2, v2, v6
	v_rcp_f32_e32 v42, v7
	s_mov_b32 s6, 0x800000
	v_fma_f32 v43, -v7, v42, 1.0
	v_fmac_f32_e32 v42, v43, v42
	v_div_scale_f32 v43, vcc, v6, v2, v6
	v_mul_f32_e32 v44, v43, v42
	v_fma_f32 v45, -v7, v44, v43
	v_fmac_f32_e32 v44, v45, v42
	v_fma_f32 v7, -v7, v44, v43
	v_div_fmas_f32 v7, v7, v42, v44
	v_div_fixup_f32 v2, v7, v2, v6
	v_pk_mul_f32 v[2:3], v[2:3], v[40:41]
	s_nop 0
	v_pk_mul_f32 v[6:7], v[2:3], v[2:3]
	s_nop 0
	v_add_f32_e32 v6, v6, v7
	v_add_f32_e32 v6, v34, v6
	v_add_f32_e32 v6, v35, v6
	v_add_f32_e32 v6, v30, v6
	v_add_f32_e32 v6, v31, v6
	v_add_f32_e32 v6, v28, v6
	v_add_f32_e32 v6, v29, v6
	ds_bpermute_b32 v7, v39, v6
	s_waitcnt lgkmcnt(0)
; DI U4 pack8(const float (&x)[8]) { return mku4(pack2(x[0], x[1]), pack2(x[2], x[3]), pack2(x[4], x[5]), pack2(x[6], x[7])); }
; DI float wave_sum(float v) { for (int o = 32; o > 0; o >>= 1) v += __shfl_xor(v, o); return v; }
; DI void phase_ssd4(PP p, int l, bool need_ctx) {
;     ...
;     ss = wave_sum(ss); float rstd = rsqrtf(ss * (1.f / 512.f) + EPS);
; #pragma unroll
;     for (int e = 0; e < 8; ++e) y[e] *= rstd * gn[lane * 8 + e];
;     *(U4*)(zx + (size_t)r * 1536 + lane * 8) = pack8(y);
	v_add_f32_e32 v6, v6, v7
	ds_bpermute_b32 v7, v38, v6
	s_waitcnt lgkmcnt(0)
	v_add_f32_e32 v6, v6, v7
	ds_bpermute_b32 v7, v37, v6
	s_waitcnt lgkmcnt(0)
	v_add_f32_e32 v6, v6, v7
	ds_bpermute_b32 v7, v36, v6
	s_waitcnt lgkmcnt(0)
	v_add_f32_e32 v6, v6, v7
	ds_bpermute_b32 v7, v17, v6
	s_waitcnt lgkmcnt(0)
	v_add_f32_e32 v6, v6, v7
	ds_bpermute_b32 v0, v0, v6
	s_waitcnt lgkmcnt(0)
	v_add_f32_e32 v0, v6, v0
	v_fmamk_f32 v0, v0, 0x3b000000, v162
	v_cmp_gt_f32_e32 vcc, s6, v0
	v_mul_f32_e32 v6, 0x4b800000, v0
	s_nop 0
	v_cndmask_b32_e32 v0, v0, v6, vcc
	v_rsq_f32_e32 v0, v0
	s_nop 0
	v_mul_f32_e32 v6, 0x45800000, v0
	v_cndmask_b32_e32 v0, v0, v6, vcc
	s_waitcnt vmcnt(0)
	v_pk_mul_f32 v[6:7], v[12:13], v[0:1] op_sel_hi:[1,0]
	v_pk_mul_f32 v[8:9], v[8:9], v[0:1] op_sel_hi:[1,0]
	v_pk_mul_f32 v[2:3], v[2:3], v[6:7]
	v_pk_mul_f32 v[6:7], v[14:15], v[0:1] op_sel_hi:[1,0]
	v_pk_mul_f32 v[4:5], v[4:5], v[8:9]
	v_pk_mul_f32 v[8:9], v[10:11], v[0:1] op_sel_hi:[1,0]
	v_pk_mul_f32 v[6:7], v[32:33], v[6:7]
	v_pk_mul_f32 v[8:9], v[26:27], v[8:9]
	v_cvt_pk_bf16_f32 v2, v2, v3
	v_cvt_pk_bf16_f32 v3, v6, v7
	v_cvt_pk_bf16_f32 v4, v4, v5
	v_cvt_pk_bf16_f32 v5, v8, v9
	global_store_dwordx4 v[24:25], v[2:5], off
	s_branch .LBB0_273
